# P0 rows: nt also on the first row's loads; default policy on the re-read b_f load
# speedup vs baseline: 1.0011x; 1.0011x over previous
.LBB0_19:
	s_or_b64 exec, exec, s[6:7]
	s_lshl_b32 s4, s87, 3
	s_ashr_i32 s3, s3, 6
	s_add_i32 s18, s3, s4
	s_lshl_b32 s20, s92, 3
	v_and_b32_e32 v45, 63, v44
	s_cmpk_lt_i32 s18, 0x4000
	s_waitcnt lgkmcnt(0)
	s_barrier
	s_cbranch_scc0 .LBB0_28
	s_add_u32 s24, s72, 0x300000
	s_addc_u32 s25, s73, 0
	s_ashr_i32 s19, s18, 31
	s_lshl_b64 s[4:5], s[18:19], 12
	s_add_u32 s4, s52, s4
	s_addc_u32 s5, s53, s5
	v_lshlrev_b32_e32 v34, 4, v45
	global_load_dwordx4 v[30:33], v34, s[4:5] nt
	global_load_dwordx4 v[26:29], v34, s[4:5] offset:1024 nt
	global_load_dwordx4 v[22:25], v34, s[4:5] offset:2048 nt
	global_load_dwordx4 v[18:21], v34, s[4:5] offset:3072 nt
	v_mbcnt_lo_u32_b32 v1, -1, 0
	v_mbcnt_hi_u32_b32 v2, -1, v1
	v_and_b32_e32 v1, 64, v2
	v_add_u32_e32 v3, 64, v1
	v_xor_b32_e32 v1, 1, v2
	v_cmp_lt_i32_e32 vcc, v1, v3
	v_xor_b32_e32 v4, 2, v2
	s_lshl_b64 s[4:5], s[18:19], 11
	v_cndmask_b32_e32 v1, v2, v1, vcc
	v_cmp_lt_i32_e32 vcc, v4, v3
	s_ashr_i32 s21, s20, 31
	v_mov_b32_e32 v35, 0
	v_cndmask_b32_e32 v4, v2, v4, vcc
	v_lshlrev_b32_e32 v46, 2, v4
	v_xor_b32_e32 v4, 4, v2
	v_cmp_lt_i32_e32 vcc, v4, v3
	v_bfe_u32 v52, v44, 2, 4
	v_lshl_or_b32 v40, v45, 3, s4
	v_cndmask_b32_e32 v4, v2, v4, vcc
	v_lshlrev_b32_e32 v47, 2, v4
	v_xor_b32_e32 v4, 8, v2
	v_cmp_lt_i32_e32 vcc, v4, v3
	v_mov_b32_e32 v41, s5
	s_lshl_b64 s[28:29], s[20:21], 11
	v_cndmask_b32_e32 v4, v2, v4, vcc
	v_lshlrev_b32_e32 v48, 2, v4
	v_xor_b32_e32 v4, 16, v2
	v_cmp_lt_i32_e32 vcc, v4, v3
	s_lshl_b64 s[4:5], s[18:19], 2
	v_lshl_add_u64 v[36:37], s[52:53], 0, v[34:35]
	v_cndmask_b32_e32 v4, v2, v4, vcc
	v_lshlrev_b32_e32 v49, 2, v4
	v_xor_b32_e32 v4, 32, v2
	v_cmp_lt_i32_e32 vcc, v4, v3
	v_add_u32_e32 v51, 0, v34
	v_lshlrev_b32_e32 v34, 2, v52
	v_cndmask_b32_e32 v2, v2, v4, vcc
	v_lshlrev_b32_e32 v50, 2, v2
	v_and_b32_e32 v2, 32, v44
	v_cmp_eq_u32_e64 s[8:9], 0, v2
	v_and_b32_e32 v2, 16, v44
	v_cmp_eq_u32_e64 s[10:11], 0, v2
	v_and_b32_e32 v2, 8, v44
	v_cmp_eq_u32_e64 s[12:13], 0, v2
	v_and_b32_e32 v2, 4, v44
	v_cmp_eq_u32_e64 s[14:15], 0, v2
	v_and_b32_e32 v2, 3, v44
	v_cmp_eq_u32_e64 s[16:17], 0, v2
	s_add_u32 s4, s4, 0x10000
	s_mov_b32 s27, 0
	v_lshlrev_b32_e32 v1, 2, v1
	v_cmp_eq_u32_e64 s[6:7], 0, v45
	v_lshl_add_u64 v[38:39], s[60:61], 0, v[34:35]
	s_addc_u32 s5, s5, 0
	s_lshl_b64 s[30:31], s[20:21], 2
	s_movk_i32 s19, 0x7fff
	s_mov_b32 s21, 0xffff0000
	s_mov_b32 s33, 0x3800000
	v_mov_b32_e32 v34, 0x358637bd
	s_mov_b32 s74, 0x800000
	s_mov_b32 s75, 0xbfb8aa3b
	s_mov_b32 s76, 0xb2a5705f
	s_mov_b32 s77, 0x42ce8ed0
	s_mov_b32 s80, 0xc2b17218
	s_mov_b32 s81, 0x7f800000
	s_mov_b32 s82, 0x3f2aaaab
	v_mov_b32_e32 v53, 0x3ecc95a3
	s_mov_b32 s83, 0x3f317218
	s_mov_b32 s85, 0x33800000
	v_mov_b32_e32 v54, 0x7f800000
	v_mov_b32_e32 v42, 0x3f317218
	s_mov_b32 s26, s18
	v_mov_b32_e32 v2, 0
	v_mov_b32_e32 v3, v35
	v_mov_b32_e32 v4, v35
	v_mov_b32_e32 v5, v35
	v_mov_b32_e32 v6, 0
	v_mov_b32_e32 v7, v35
	v_mov_b32_e32 v8, v35
	v_mov_b32_e32 v9, v35
	v_mov_b32_e32 v10, 0
	v_mov_b32_e32 v11, v35
	v_mov_b32_e32 v12, v35
	v_mov_b32_e32 v13, v35
	v_mov_b32_e32 v14, 0
	v_mov_b32_e32 v15, v35
	v_mov_b32_e32 v16, v35
	v_mov_b32_e32 v17, v35
	s_branch .LBB0_22
